# k=6 OpMerge<0> epilogue: all 16 gate quads loaded before the first store, so no wait in the store loop depends on earlier stores
# baseline (speedup 1.0000x reference)
;     __device__ __forceinline__ void operator()(int row, int col, f32x4 v0, f32x4 v1) const { *(u32x4*)(G + (size_t)row * 1024 + col) = pack8(v0, v1); }
;     __device__ __forceinline__ void operator()(const pg8::f32x4 (&acc)[2][2][4][2], const pg8::Unit& u, int wr, int wc, int fr, int fq) const {
;     ...
;         for (int ai = 0; ai < 2; ++ai)
; #pragma unroll
;             for (int m = 0; m < 4; ++m)
; #pragma unroll
;                 for (int bj = 0; bj < 2; ++bj) { op(row0 + ai * 128 + m * 16, col0 + bj * 128, acc[ai][bj][m][0], acc[ai][bj][m][1]); asm volatile("" ::: "memory"); }
;     __device__ __forceinline__ void operator()(int row, int col, f32x4 v0, f32x4 v1) const {
;         f32x4 g0, g1; unpack8(*(const u32x4*)(GT + (size_t)row * 3072 + KB * 1024 + col), g0, g1);
;         float* mf = MF + (size_t)row * 1024 + col;
;         f32x4 r0 = g0 * v0, r1 = g1 * v1;
;         if (KB > 0) { r0 += *(const f32x4*)mf; r1 += *(const f32x4*)(mf + 4); }
;         if (KB < 2) { *(f32x4*)mf = r0; *(f32x4*)(mf + 4) = r1; }
.LBB0_180:
	v_mul_u32_u24_e32 v165, 0x1800, v161
	v_lshl_add_u32 v165, v163, 1, v165
	v_lshlrev_b32_e32 v170, 12, v161
	v_lshl_add_u32 v170, v163, 2, v170
	s_mul_i32 vcc_lo, s95, 0x180000
	s_lshl_b32 vcc_hi, s94, 9
	s_add_u32 vcc_lo, vcc_lo, vcc_hi
	s_add_u32 s4, s48, vcc_lo
	s_addc_u32 s5, s49, 0
	s_lshl_b32 vcc_lo, s95, 20
	s_lshl_b32 vcc_hi, s94, 10
	s_add_u32 vcc_lo, vcc_lo, vcc_hi
	s_add_u32 s6, s50, vcc_lo
	s_addc_u32 s7, s51, 0
	s_mov_b64 s[98:99], s[6:7]
	global_load_dwordx4 v[198:201], v165, s[4:5]
	global_load_dwordx4 v[202:205], v165, s[4:5] offset:256
	s_add_u32 s4, s4, 0x18000
	s_addc_u32 s5, s5, 0
	global_load_dwordx4 v[206:209], v165, s[4:5]
	global_load_dwordx4 v[210:213], v165, s[4:5] offset:256
	s_add_u32 s4, s4, 0x18000
	s_addc_u32 s5, s5, 0
	global_load_dwordx4 v[214:217], v165, s[4:5]
	global_load_dwordx4 v[218:221], v165, s[4:5] offset:256
	s_add_u32 s4, s4, 0x18000
	s_addc_u32 s5, s5, 0
	global_load_dwordx4 v[222:225], v165, s[4:5]
	global_load_dwordx4 v[226:229], v165, s[4:5] offset:256
	s_add_u32 s4, s4, 0x78000
	s_addc_u32 s5, s5, 0
	global_load_dwordx4 v[230:233], v165, s[4:5]
	global_load_dwordx4 v[234:237], v165, s[4:5] offset:256
	s_add_u32 s4, s4, 0x18000
	s_addc_u32 s5, s5, 0
	global_load_dwordx4 v[238:241], v165, s[4:5]
	global_load_dwordx4 v[242:245], v165, s[4:5] offset:256
	s_add_u32 s4, s4, 0x18000
	s_addc_u32 s5, s5, 0
	global_load_dwordx4 v[166:169], v165, s[4:5]
	global_load_dwordx4 v[174:177], v165, s[4:5] offset:256
	s_add_u32 s4, s4, 0x18000
	s_addc_u32 s5, s5, 0
	global_load_dwordx4 v[182:185], v165, s[4:5]
	global_load_dwordx4 v[246:249], v165, s[4:5] offset:256
	s_waitcnt vmcnt(15)
	v_lshlrev_b32_e32 v140, 16, v198
	v_and_b32_e32 v141, 0xffff0000, v198
	v_lshlrev_b32_e32 v142, 16, v199
	v_and_b32_e32 v143, 0xffff0000, v199
	v_lshlrev_b32_e32 v144, 16, v200
	v_and_b32_e32 v145, 0xffff0000, v200
	v_lshlrev_b32_e32 v146, 16, v201
	v_and_b32_e32 v147, 0xffff0000, v201
	v_pk_mul_f32 v[126:127], v[126:127], v[140:141]
	v_pk_mul_f32 v[128:129], v[128:129], v[142:143]
	v_pk_mul_f32 v[122:123], v[122:123], v[144:145]
	v_pk_mul_f32 v[124:125], v[124:125], v[146:147]
	global_store_dwordx4 v170, v[126:129], s[98:99]
	global_store_dwordx4 v170, v[122:125], s[98:99] offset:16
	s_waitcnt vmcnt(16)
	v_lshlrev_b32_e32 v140, 16, v202
	v_and_b32_e32 v141, 0xffff0000, v202
	v_lshlrev_b32_e32 v142, 16, v203
	v_and_b32_e32 v143, 0xffff0000, v203
	v_lshlrev_b32_e32 v144, 16, v204
	v_and_b32_e32 v145, 0xffff0000, v204
	v_lshlrev_b32_e32 v146, 16, v205
	v_and_b32_e32 v147, 0xffff0000, v205
	v_pk_mul_f32 v[118:119], v[118:119], v[140:141]
	v_pk_mul_f32 v[120:121], v[120:121], v[142:143]
	v_pk_mul_f32 v[114:115], v[114:115], v[144:145]
	v_pk_mul_f32 v[116:117], v[116:117], v[146:147]
	global_store_dwordx4 v170, v[118:121], s[98:99] offset:512
	global_store_dwordx4 v170, v[114:117], s[98:99] offset:528
	s_waitcnt vmcnt(17)
	v_lshlrev_b32_e32 v140, 16, v206
	v_and_b32_e32 v141, 0xffff0000, v206
	v_lshlrev_b32_e32 v142, 16, v207
	v_and_b32_e32 v143, 0xffff0000, v207
	v_lshlrev_b32_e32 v144, 16, v208
	v_and_b32_e32 v145, 0xffff0000, v208
	v_lshlrev_b32_e32 v146, 16, v209
	v_and_b32_e32 v147, 0xffff0000, v209
	v_pk_mul_f32 v[110:111], v[110:111], v[140:141]
	v_pk_mul_f32 v[112:113], v[112:113], v[142:143]
	v_pk_mul_f32 v[106:107], v[106:107], v[144:145]
	v_pk_mul_f32 v[108:109], v[108:109], v[146:147]
	s_add_u32 s98, s98, 0x10000
	s_addc_u32 s99, s99, 0
	global_store_dwordx4 v170, v[110:113], s[98:99]
	global_store_dwordx4 v170, v[106:109], s[98:99] offset:16
	s_waitcnt vmcnt(18)
	v_lshlrev_b32_e32 v140, 16, v210
	v_and_b32_e32 v141, 0xffff0000, v210
	v_lshlrev_b32_e32 v142, 16, v211
	v_and_b32_e32 v143, 0xffff0000, v211
	v_lshlrev_b32_e32 v144, 16, v212
	v_and_b32_e32 v145, 0xffff0000, v212
	v_lshlrev_b32_e32 v146, 16, v213
	v_and_b32_e32 v147, 0xffff0000, v213
	v_pk_mul_f32 v[102:103], v[102:103], v[140:141]
	v_pk_mul_f32 v[104:105], v[104:105], v[142:143]
	v_pk_mul_f32 v[98:99], v[98:99], v[144:145]
	v_pk_mul_f32 v[100:101], v[100:101], v[146:147]
	global_store_dwordx4 v170, v[102:105], s[98:99] offset:512
	global_store_dwordx4 v170, v[98:101], s[98:99] offset:528
	s_waitcnt vmcnt(19)
	v_lshlrev_b32_e32 v140, 16, v214
	v_and_b32_e32 v141, 0xffff0000, v214
	v_lshlrev_b32_e32 v142, 16, v215
	v_and_b32_e32 v143, 0xffff0000, v215
	v_lshlrev_b32_e32 v144, 16, v216
	v_and_b32_e32 v145, 0xffff0000, v216
	v_lshlrev_b32_e32 v146, 16, v217
	v_and_b32_e32 v147, 0xffff0000, v217
	v_pk_mul_f32 v[94:95], v[94:95], v[140:141]
	v_pk_mul_f32 v[96:97], v[96:97], v[142:143]
	v_pk_mul_f32 v[90:91], v[90:91], v[144:145]
	v_pk_mul_f32 v[92:93], v[92:93], v[146:147]
	s_add_u32 s98, s98, 0x10000
	s_addc_u32 s99, s99, 0
	global_store_dwordx4 v170, v[94:97], s[98:99]
	global_store_dwordx4 v170, v[90:93], s[98:99] offset:16
	s_waitcnt vmcnt(20)
	v_lshlrev_b32_e32 v140, 16, v218
	v_and_b32_e32 v141, 0xffff0000, v218
	v_lshlrev_b32_e32 v142, 16, v219
	v_and_b32_e32 v143, 0xffff0000, v219
	v_lshlrev_b32_e32 v144, 16, v220
	v_and_b32_e32 v145, 0xffff0000, v220
	v_lshlrev_b32_e32 v146, 16, v221
	v_and_b32_e32 v147, 0xffff0000, v221
	v_pk_mul_f32 v[86:87], v[86:87], v[140:141]
	v_pk_mul_f32 v[88:89], v[88:89], v[142:143]
	v_pk_mul_f32 v[82:83], v[82:83], v[144:145]
	v_pk_mul_f32 v[84:85], v[84:85], v[146:147]
	global_store_dwordx4 v170, v[86:89], s[98:99] offset:512
	global_store_dwordx4 v170, v[82:85], s[98:99] offset:528
	s_waitcnt vmcnt(21)
;     __device__ __forceinline__ void operator()(int row, int col, f32x4 v0, f32x4 v1) const { *(u32x4*)(G + (size_t)row * 1024 + col) = pack8(v0, v1); }
;     __device__ __forceinline__ void operator()(const pg8::f32x4 (&acc)[2][2][4][2], const pg8::Unit& u, int wr, int wc, int fr, int fq) const {
;     ...
;         for (int ai = 0; ai < 2; ++ai)
; #pragma unroll
;             for (int m = 0; m < 4; ++m)
; #pragma unroll
;                 for (int bj = 0; bj < 2; ++bj) { op(row0 + ai * 128 + m * 16, col0 + bj * 128, acc[ai][bj][m][0], acc[ai][bj][m][1]); asm volatile("" ::: "memory"); }
;     __device__ __forceinline__ void operator()(int row, int col, f32x4 v0, f32x4 v1) const {
;         f32x4 g0, g1; unpack8(*(const u32x4*)(GT + (size_t)row * 3072 + KB * 1024 + col), g0, g1);
;         float* mf = MF + (size_t)row * 1024 + col;
;         f32x4 r0 = g0 * v0, r1 = g1 * v1;
;         if (KB > 0) { r0 += *(const f32x4*)mf; r1 += *(const f32x4*)(mf + 4); }
;         if (KB < 2) { *(f32x4*)mf = r0; *(f32x4*)(mf + 4) = r1; }
	v_lshlrev_b32_e32 v140, 16, v222
	v_and_b32_e32 v141, 0xffff0000, v222
	v_lshlrev_b32_e32 v142, 16, v223
	v_and_b32_e32 v143, 0xffff0000, v223
	v_lshlrev_b32_e32 v144, 16, v224
	v_and_b32_e32 v145, 0xffff0000, v224
	v_lshlrev_b32_e32 v146, 16, v225
	v_and_b32_e32 v147, 0xffff0000, v225
	v_pk_mul_f32 v[78:79], v[78:79], v[140:141]
	v_pk_mul_f32 v[80:81], v[80:81], v[142:143]
	v_pk_mul_f32 v[74:75], v[74:75], v[144:145]
	v_pk_mul_f32 v[76:77], v[76:77], v[146:147]
	s_add_u32 s98, s98, 0x10000
	s_addc_u32 s99, s99, 0
	global_store_dwordx4 v170, v[78:81], s[98:99]
	global_store_dwordx4 v170, v[74:77], s[98:99] offset:16
	s_waitcnt vmcnt(22)
	v_lshlrev_b32_e32 v140, 16, v226
	v_and_b32_e32 v141, 0xffff0000, v226
	v_lshlrev_b32_e32 v142, 16, v227
	v_and_b32_e32 v143, 0xffff0000, v227
	v_lshlrev_b32_e32 v144, 16, v228
	v_and_b32_e32 v145, 0xffff0000, v228
	v_lshlrev_b32_e32 v146, 16, v229
	v_and_b32_e32 v147, 0xffff0000, v229
	v_pk_mul_f32 v[70:71], v[70:71], v[140:141]
	v_pk_mul_f32 v[72:73], v[72:73], v[142:143]
	v_pk_mul_f32 v[66:67], v[66:67], v[144:145]
	v_pk_mul_f32 v[68:69], v[68:69], v[146:147]
	global_store_dwordx4 v170, v[70:73], s[98:99] offset:512
	global_store_dwordx4 v170, v[66:69], s[98:99] offset:528
	s_waitcnt vmcnt(23)
	v_lshlrev_b32_e32 v140, 16, v230
	v_and_b32_e32 v141, 0xffff0000, v230
	v_lshlrev_b32_e32 v142, 16, v231
	v_and_b32_e32 v143, 0xffff0000, v231
	v_lshlrev_b32_e32 v144, 16, v232
	v_and_b32_e32 v145, 0xffff0000, v232
	v_lshlrev_b32_e32 v146, 16, v233
	v_and_b32_e32 v147, 0xffff0000, v233
	v_pk_mul_f32 v[62:63], v[62:63], v[140:141]
	v_pk_mul_f32 v[64:65], v[64:65], v[142:143]
	v_pk_mul_f32 v[58:59], v[58:59], v[144:145]
	v_pk_mul_f32 v[60:61], v[60:61], v[146:147]
	s_add_u32 s98, s98, 0x50000
	s_addc_u32 s99, s99, 0
	global_store_dwordx4 v170, v[62:65], s[98:99]
	global_store_dwordx4 v170, v[58:61], s[98:99] offset:16
	s_waitcnt vmcnt(24)
	v_lshlrev_b32_e32 v140, 16, v234
	v_and_b32_e32 v141, 0xffff0000, v234
	v_lshlrev_b32_e32 v142, 16, v235
	v_and_b32_e32 v143, 0xffff0000, v235
	v_lshlrev_b32_e32 v144, 16, v236
	v_and_b32_e32 v145, 0xffff0000, v236
	v_lshlrev_b32_e32 v146, 16, v237
	v_and_b32_e32 v147, 0xffff0000, v237
	v_pk_mul_f32 v[54:55], v[54:55], v[140:141]
	v_pk_mul_f32 v[56:57], v[56:57], v[142:143]
	v_pk_mul_f32 v[50:51], v[50:51], v[144:145]
	v_pk_mul_f32 v[52:53], v[52:53], v[146:147]
	global_store_dwordx4 v170, v[54:57], s[98:99] offset:512
	global_store_dwordx4 v170, v[50:53], s[98:99] offset:528
	s_waitcnt vmcnt(25)
	v_lshlrev_b32_e32 v140, 16, v238
	v_and_b32_e32 v141, 0xffff0000, v238
	v_lshlrev_b32_e32 v142, 16, v239
	v_and_b32_e32 v143, 0xffff0000, v239
	v_lshlrev_b32_e32 v144, 16, v240
	v_and_b32_e32 v145, 0xffff0000, v240
	v_lshlrev_b32_e32 v146, 16, v241
	v_and_b32_e32 v147, 0xffff0000, v241
	v_pk_mul_f32 v[46:47], v[46:47], v[140:141]
	v_pk_mul_f32 v[48:49], v[48:49], v[142:143]
	v_pk_mul_f32 v[42:43], v[42:43], v[144:145]
	v_pk_mul_f32 v[44:45], v[44:45], v[146:147]
	s_add_u32 s98, s98, 0x10000
	s_addc_u32 s99, s99, 0
	global_store_dwordx4 v170, v[46:49], s[98:99]
	global_store_dwordx4 v170, v[42:45], s[98:99] offset:16
	s_waitcnt vmcnt(26)
	v_lshlrev_b32_e32 v140, 16, v242
	v_and_b32_e32 v141, 0xffff0000, v242
	v_lshlrev_b32_e32 v142, 16, v243
	v_and_b32_e32 v143, 0xffff0000, v243
	v_lshlrev_b32_e32 v144, 16, v244
	v_and_b32_e32 v145, 0xffff0000, v244
	v_lshlrev_b32_e32 v146, 16, v245
	v_and_b32_e32 v147, 0xffff0000, v245
	v_pk_mul_f32 v[38:39], v[38:39], v[140:141]
	v_pk_mul_f32 v[40:41], v[40:41], v[142:143]
	v_pk_mul_f32 v[34:35], v[34:35], v[144:145]
	v_pk_mul_f32 v[36:37], v[36:37], v[146:147]
	global_store_dwordx4 v170, v[38:41], s[98:99] offset:512
	global_store_dwordx4 v170, v[34:37], s[98:99] offset:528
	s_waitcnt vmcnt(27)
	v_lshlrev_b32_e32 v140, 16, v166
	v_and_b32_e32 v141, 0xffff0000, v166
	v_lshlrev_b32_e32 v142, 16, v167
	v_and_b32_e32 v143, 0xffff0000, v167
	v_lshlrev_b32_e32 v144, 16, v168
	v_and_b32_e32 v145, 0xffff0000, v168
	v_lshlrev_b32_e32 v146, 16, v169
	v_and_b32_e32 v147, 0xffff0000, v169
	v_pk_mul_f32 v[30:31], v[30:31], v[140:141]
	v_pk_mul_f32 v[32:33], v[32:33], v[142:143]
	v_pk_mul_f32 v[26:27], v[26:27], v[144:145]
	v_pk_mul_f32 v[28:29], v[28:29], v[146:147]
	s_add_u32 s98, s98, 0x10000
	s_addc_u32 s99, s99, 0
	global_store_dwordx4 v170, v[30:33], s[98:99]
	global_store_dwordx4 v170, v[26:29], s[98:99] offset:16
	s_waitcnt vmcnt(28)
	v_lshlrev_b32_e32 v140, 16, v174
	v_and_b32_e32 v141, 0xffff0000, v174
	v_lshlrev_b32_e32 v142, 16, v175
	v_and_b32_e32 v143, 0xffff0000, v175
	v_lshlrev_b32_e32 v144, 16, v176
	v_and_b32_e32 v145, 0xffff0000, v176
	v_lshlrev_b32_e32 v146, 16, v177
	v_and_b32_e32 v147, 0xffff0000, v177
	v_pk_mul_f32 v[22:23], v[22:23], v[140:141]
	v_pk_mul_f32 v[24:25], v[24:25], v[142:143]
	v_pk_mul_f32 v[18:19], v[18:19], v[144:145]
	v_pk_mul_f32 v[20:21], v[20:21], v[146:147]
	global_store_dwordx4 v170, v[22:25], s[98:99] offset:512
	global_store_dwordx4 v170, v[18:21], s[98:99] offset:528
	s_waitcnt vmcnt(29)
	v_lshlrev_b32_e32 v140, 16, v182
	v_and_b32_e32 v141, 0xffff0000, v182
	v_lshlrev_b32_e32 v142, 16, v183
	v_and_b32_e32 v143, 0xffff0000, v183
	v_lshlrev_b32_e32 v144, 16, v184
	v_and_b32_e32 v145, 0xffff0000, v184
	v_lshlrev_b32_e32 v146, 16, v185
	v_and_b32_e32 v147, 0xffff0000, v185
	v_pk_mul_f32 v[14:15], v[14:15], v[140:141]
	v_pk_mul_f32 v[16:17], v[16:17], v[142:143]
	v_pk_mul_f32 v[10:11], v[10:11], v[144:145]
	v_pk_mul_f32 v[12:13], v[12:13], v[146:147]
	s_add_u32 s98, s98, 0x10000
	s_addc_u32 s99, s99, 0
	global_store_dwordx4 v170, v[14:17], s[98:99]
	global_store_dwordx4 v170, v[10:13], s[98:99] offset:16
	s_waitcnt vmcnt(30)
	v_lshlrev_b32_e32 v140, 16, v246
	v_and_b32_e32 v141, 0xffff0000, v246
	v_lshlrev_b32_e32 v142, 16, v247
	v_and_b32_e32 v143, 0xffff0000, v247
	v_lshlrev_b32_e32 v144, 16, v248
	v_and_b32_e32 v145, 0xffff0000, v248
	v_lshlrev_b32_e32 v146, 16, v249
	v_and_b32_e32 v147, 0xffff0000, v249
	v_pk_mul_f32 v[6:7], v[6:7], v[140:141]
	v_pk_mul_f32 v[8:9], v[8:9], v[142:143]
	v_pk_mul_f32 v[2:3], v[2:3], v[144:145]
	v_pk_mul_f32 v[4:5], v[4:5], v[146:147]
	global_store_dwordx4 v170, v[6:9], s[98:99] offset:512
	global_store_dwordx4 v170, v[2:5], s[98:99] offset:528
	s_and_b64 vcc, exec, s[40:41]
	s_mov_b64 s[4:5], -1
	s_cbranch_vccnz .LBB0_168
	s_andn2_b64 vcc, exec, s[56:57]
	s_cbranch_vccnz .LBB0_167
	s_barrier
	s_branch .LBB0_167
